# v53 + up GEMM only: trailing half prioritised inside the K-loop, leading half prioritised inside the epilogue (priority flipped at epilogue entry/exit)
# speedup vs baseline: 1.0063x; 1.0034x over previous
; __device__ __forceinline__ int mk_lane() { int l; asm volatile("v_mbcnt_lo_u32_b32 %0, -1, 0\n\tv_mbcnt_hi_u32_b32 %0, -1, %0" : "=v"(l)); return l; }
; template <class Prob, class Epi, bool I8 = false, bool ALIGN_EPI = true, bool SP2 = true>
; __device__ __forceinline__ void gemm_phase(LAS unsigned char* lds, int wave, const Prob& P, const Epi& E) {
;     const int tid_ = wave * 64 + mk_lane();
;     const int tid = tid_, wid = __builtin_amdgcn_readfirstlane(tid >> 6), lane = tid & 63, wr = wid >> 2, wc = wid & 3, fr = lane & 15, fq = lane >> 4;
;     const int K = P.K, nt = K / BK;
;     unsigned voffA[2], voffB[2];
; #pragma unroll
;     for (int i = 0; i < 2; ++i) { int R, C; stage_rc(tid * 16 + i * 8192, R, C); const int Rb = (R & ~31) + perm32(R & 31);
;         voffA[i] = P.a_rowoff(R) + (unsigned)C * 2u; voffB[i] = P.b_rowoff(Rb) + (unsigned)C * 2u; }
;     const size_t kstep = (size_t)(BK * 2);
;     const size_t hstepA = P.a_hstep(), hstepB = P.b_hstep();
;     const unsigned ldsw = (unsigned)wid * 1024u;
;     const unsigned ldsb = (unsigned)(size_t)lds + ldsw;
;     const int aoff = lds_byte(wr * 64 + fr, fq * 8), boff = lds_byte(wc * 32 + fr, fq * 8);
;     ...
;     Unit cur, nxt; int ui = 0;
;     if (!P.next(0, cur)) return;
;     Acc acc;
; #pragma unroll
;     for (int a = 0; a < 2; ++a)
; #pragma unroll
;         for (int b = 0; b < 2; ++b)
; #pragma unroll
;             for (int m = 0; m < 4; ++m)
; #pragma unroll
;                 for (int n = 0; n < 2; ++n) acc[a][b][m][n] = (f32x4){0.f, 0.f, 0.f, 0.f};
;     h16x8 At[4][2], B0[2][2], B1[2][2];
;     const char* cA = P.a_tile(cur); const char* cB = P.b_tile(cur);
;     if constexpr (SP2) {
;         PG8_STAGE(PG8_SB(0, 0), cB, voffB); PG8_STAGE(PG8_SB(0, 1), cB + hstepB, voffB); PG8_STAGE(PG8_SA(0, 0), cA, voffA); PG8_STAGE(PG8_SA(0, 1), cA + hstepA, voffA);
;         if (wr == 1) PG8_BAR;
;         PG8_WAIT_V(2); PG8_BAR;
;         PG8_STAGE(PG8_SB(1, 0), cB + kstep, voffB); PG8_STAGE(PG8_SA(1, 0), cA + kstep, voffA); PG8_STAGE(PG8_SB(1, 1), cB + hstepB + kstep, voffB);
;         PG8_WAIT_V(6); PG8_BAR;
;     } else {
;         PG8_STAGE(PG8_SB(0, 0), cB, voffB); PG8_STAGE(PG8_SA(0, 0), cA, voffA); PG8_STAGE(PG8_SB(0, 1), cB + hstepB, voffB); PG8_STAGE(PG8_SA(0, 1), cA + hstepA, voffA);
;         if (wr == 1) PG8_BAR;
;         PG8_WAIT_V(4); PG8_BAR;
.LBB0_1056:
	v_readlane_b32 s0, v254, 42
	v_readlane_b32 s4, v252, 23
	s_waitcnt lgkmcnt(0)
	s_barrier
	s_add_u32 s14, s30, 0x2d200000
	v_mbcnt_lo_u32_b32 v0, -1, 0
	v_mbcnt_hi_u32_b32 v0, -1, v0
	v_readlane_b32 s5, v252, 24
	v_add_u32_e32 v1, s0, v0
	s_addc_u32 s15, s31, 0
	v_readfirstlane_b32 s0, v1
	s_and_b64 vcc, exec, s[4:5]
	s_cbranch_vccz .LBB0_1088
	v_ashrrev_i32_e32 v3, 31, v1
	v_lshrrev_b32_e32 v3, 26, v3
	v_lshlrev_b32_e32 v2, 4, v1
	v_add_u32_e32 v3, v1, v3
	v_bfe_i32 v1, v1, 27, 1
	v_lshrrev_b32_e32 v1, 22, v1
	v_add_u32_e32 v1, v2, v1
	v_and_b32_e32 v1, 0xfffffc00, v1
	v_sub_u32_e32 v1, v2, v1
	v_lshrrev_b32_e32 v4, 4, v1
	v_bitop3_b32 v1, v4, v1, 32 bitop3:0x6c
	v_ashrrev_i32_e32 v5, 31, v1
	v_ashrrev_i32_e32 v3, 6, v3
	v_lshrrev_b32_e32 v5, 26, v5
	v_lshlrev_b32_e32 v4, 3, v3
	v_add_u32_e32 v5, v1, v5
	v_and_b32_e32 v4, -16, v4
	v_ashrrev_i32_e32 v6, 6, v5
	v_add_u32_e32 v4, v6, v4
	v_and_b32_e32 v5, 0xc0, v5
	v_sub_u32_e32 v1, v1, v5
	v_lshlrev_b32_e32 v5, 1, v4
	v_lshrrev_b32_e32 v8, 2, v4
	v_and_b32_e32 v6, 3, v6
	s_mov_b32 s1, 0x1fffe0
	v_mov_b32_e32 v9, 1
	v_and_b32_e32 v7, 24, v5
	v_and_b32_e32 v8, 4, v8
	v_and_or_b32 v6, v4, s1, v6
	v_lshlrev_b32_e32 v3, 5, v3
	v_ashrrev_i16_sdwa v1, v9, sext(v1) dst_sel:DWORD dst_unused:UNUSED_PAD src0_sel:DWORD src1_sel:BYTE_0
	v_or3_b32 v6, v6, v8, v7
	v_lshlrev_b32_e32 v7, 3, v4
	v_and_b32_e32 v3, 32, v3
	v_bfe_i32 v1, v1, 0, 16
	v_and_b32_e32 v5, 0x1fff80, v5
	v_and_b32_e32 v7, 0x78, v7
	v_bfe_u32 v4, v4, 4, 2
	v_or3_b32 v4, v5, v7, v4
	v_add_lshl_u32 v1, v3, v1, 1
	v_lshl_add_u32 v250, v4, 11, v1
	v_lshl_add_u32 v217, v6, 11, v1
	v_add_u32_e32 v1, 0x2000, v2
	v_ashrrev_i32_e32 v2, 31, v1
	v_lshrrev_b32_e32 v2, 22, v2
	v_add_u32_e32 v2, v1, v2
	v_ashrrev_i32_e32 v2, 10, v2
	v_mul_i32_i24_e32 v3, 0x400, v2
	v_sub_u32_e32 v1, v1, v3
	v_lshrrev_b32_e32 v3, 4, v1
	v_bitop3_b32 v1, v3, v1, 32 bitop3:0x6c
	v_ashrrev_i32_e32 v4, 31, v1
	v_lshrrev_b32_e32 v4, 26, v4
	v_lshlrev_b32_e32 v3, 3, v2
	v_add_u32_e32 v4, v1, v4
	v_and_b32_e32 v3, -16, v3
	v_ashrrev_i32_e32 v5, 6, v4
	v_add_u32_e32 v3, v5, v3
	v_and_b32_e32 v5, 3, v5
	v_and_b32_e32 v4, 0xc0, v4
	v_and_or_b32 v5, v3, s1, v5
	s_ashr_i32 s1, s0, 6
	v_sub_u32_e32 v1, v1, v4
	s_lshl_b32 s2, s1, 10
	s_ashr_i32 s64, s0, 8
	v_lshlrev_b32_e32 v2, 5, v2
	v_ashrrev_i16_sdwa v1, v9, sext(v1) dst_sel:DWORD dst_unused:UNUSED_PAD src0_sel:DWORD src1_sel:BYTE_0
	v_lshlrev_b32_e32 v4, 1, v3
	v_lshrrev_b32_e32 v7, 2, v3
	s_add_i32 s72, s2, 0
	v_readlane_b32 s4, v252, 48
	v_and_b32_e32 v2, 32, v2
	v_bfe_i32 v1, v1, 0, 16
	v_and_b32_e32 v6, 24, v4
	v_and_b32_e32 v7, 4, v7
	v_readlane_b32 s5, v252, 49
	s_add_u32 s44, s79, s4
	v_or3_b32 v5, v5, v7, v6
	v_add_lshl_u32 v1, v2, v1, 1
	s_addc_u32 s45, s40, s5
	s_add_i32 s73, s72, 0x10000
	s_mov_b32 s2, m0
	s_mov_b32 m0, s73
	s_nop 0
	global_load_lds_dwordx4 v217, s[44:45]
	s_mov_b32 m0, s2
	s_add_i32 s74, s72, 0x12000
	v_lshl_add_u32 v248, v5, 11, v1
	s_mov_b32 s2, m0
	s_mov_b32 m0, s74
	s_nop 0
	global_load_lds_dwordx4 v248, s[44:45]
	s_mov_b32 m0, s2
	s_add_u32 s4, s44, 0x40000
	s_addc_u32 s5, s45, 0
	s_add_i32 s75, s72, 0x14000
	s_mov_b32 s2, m0
	s_mov_b32 m0, s75
	s_nop 0
	global_load_lds_dwordx4 v217, s[4:5]
	s_mov_b32 m0, s2
	v_lshlrev_b32_e32 v6, 3, v3
	s_add_i32 s80, s72, 0x16000
	s_mov_b32 s2, m0
	s_mov_b32 m0, s80
	s_nop 0
	global_load_lds_dwordx4 v248, s[4:5]
	s_mov_b32 m0, s2
	v_readlane_b32 s4, v252, 56
	v_and_b32_e32 v4, 0x1fff80, v4
	v_and_b32_e32 v6, 0x78, v6
	v_bfe_u32 v3, v3, 4, 2
	v_readlane_b32 s5, v252, 57
	s_add_u32 s60, s41, s4
	v_or3_b32 v3, v4, v6, v3
	s_addc_u32 s61, s19, s5
	s_mov_b32 s2, m0
	s_mov_b32 m0, s72
	s_nop 0
	global_load_lds_dwordx4 v250, s[60:61]
	s_mov_b32 m0, s2
	s_add_i32 s81, s72, 0x2000
	v_lshl_add_u32 v247, v3, 11, v1
	s_mov_b32 s2, m0
	s_mov_b32 m0, s81
	s_nop 0
	global_load_lds_dwordx4 v247, s[60:61]
	s_mov_b32 m0, s2
	s_add_u32 s4, s60, 0x2000
	s_addc_u32 s5, s61, 0
	s_add_i32 s82, s72, 0x4000
	s_mov_b32 s2, m0
	s_mov_b32 m0, s82
	s_nop 0
	global_load_lds_dwordx4 v250, s[4:5]
	s_mov_b32 m0, s2
	s_add_i32 s83, s72, 0x6000
	s_mov_b32 s2, m0
	s_mov_b32 m0, s83
	s_nop 0
	global_load_lds_dwordx4 v247, s[4:5]
	s_mov_b32 m0, s2
	s_cmp_eq_u32 s64, 1
	s_cselect_b64 s[16:17], -1, 0
	s_setprio 0
	s_cmp_lg_u32 s64, 1
	s_cbranch_scc1 .LBB0_1059
	s_barrier
	s_setprio 1

; __device__ __forceinline__ int mk_lane() { int l; asm volatile("v_mbcnt_lo_u32_b32 %0, -1, 0\n\tv_mbcnt_hi_u32_b32 %0, -1, %0" : "=v"(l)); return l; }
; #define PG8_BAR __builtin_amdgcn_s_barrier()
; template <class Prob, class Epi, bool I8 = false, bool ALIGN_EPI = true, bool SP2 = true>
; __device__ __forceinline__ void gemm_phase(LAS unsigned char* lds, int wave, const Prob& P, const Epi& E) {
;     ...
;         if constexpr (ALIGN_EPI) { if (wr == 0) PG8_BAR; }
;         { const int l_tid = wave * 64 + mk_lane();
;           const int l_lane = l_tid & 63; E(acc, cur, wr, wc, l_lane & 15, l_lane >> 4, lds, l_tid); }
.LBB0_1068:
	s_cmp_eq_u64 s[46:47], 0
	s_cbranch_scc1 .Lpe_w1
	s_setprio 1
	s_branch .Lpe_done
.Lpe_w1:
	s_setprio 0

; __device__ __forceinline__ float silu_f(float x) { return x * __builtin_amdgcn_rcpf(1.0f + __expf(-x)); }
;     __device__ __forceinline__ void operator()(Acc& acc, const Unit& u, int wr, int wc, int fr, int fq, LAS unsigned char* lds, int tid) const {
;     ...
;         for (int ai = 0; ai < 2; ++ai)
; #pragma unroll
;             for (int m = 0; m < 4; ++m) {
;                 f32x4 a[2];
; #pragma unroll
;                 for (int n = 0; n < 2; ++n)
; #pragma unroll
;                     for (int e = 0; e < 4; ++e) a[n][e] = silu_f(acc[ai][0][m][n][e]) * acc[ai][1][m][n][e];
;                 store_h8_nt((h16*)((char*)ACT + (((tok0 + tl0 + 4u * ai + m) * (unsigned)FF + colo) << 1)), a[0], a[1]);
.Lh1065_skip:
	v_pk_add_f32 v[136:137], v[136:137], 1.0 op_sel_hi:[1,0]
	v_add_lshl_u32 v104, v104, v213, 1
	v_cvt_pk_f16_f32 v115, v132, v133
	v_cvt_pk_f16_f32 v116, v116, v117
	v_cvt_pk_f16_f32 v117, v118, v119
	v_rcp_f32_e32 v106, v136
	v_pk_mul_f32 v[118:119], v[130:131], s[100:101] op_sel_hi:[1,0]
	v_exp_f32_e32 v118, v118
	v_exp_f32_e32 v119, v119
	global_store_dwordx4 v104, v[114:117], s[14:15] nt
	v_pk_mul_f32 v[146:147], v[82:83], v[192:193]
	v_mov_b32_dpp v110, v126 row_shl:1 row_mask:0xf bank_mask:0xf
	v_rcp_f32_e32 v107, v137
	v_pk_add_f32 v[118:119], v[118:119], 1.0 op_sel_hi:[1,0]
	v_rcp_f32_e32 v114, v118
	v_rcp_f32_e32 v115, v119
	v_pk_mul_f32 v[132:133], v[144:145], s[100:101] op_sel_hi:[1,0]
	v_exp_f32_e32 v132, v132
	v_exp_f32_e32 v133, v133
	v_pk_fma_f32 v[146:147], v[232:233], v[162:163], v[146:147]
	v_pk_mul_f32 v[114:115], v[130:131], v[114:115]
	v_pk_add_f32 v[132:133], v[132:133], 1.0 op_sel_hi:[1,0]
	v_pk_fma_f32 v[146:147], v[74:75], v[166:167], v[146:147]
	v_pk_mul_f32 v[116:117], v[114:115], v[178:179]
	v_rcp_f32_e32 v114, v132
	v_rcp_f32_e32 v115, v133
	v_pk_mul_f32 v[130:131], v[146:147], s[100:101] op_sel_hi:[1,0]
	v_exp_f32_e32 v130, v130
	v_exp_f32_e32 v131, v131
	v_pk_mul_f32 v[106:107], v[128:129], v[106:107]
	v_pk_mul_f32 v[118:119], v[112:113], v[20:21]
	v_pk_mul_f32 v[114:115], v[144:145], v[114:115]
	v_pk_fma_f32 v[118:119], v[134:135], v[18:19], v[118:119]
	v_pk_add_f32 v[130:131], v[130:131], 1.0 op_sel_hi:[1,0]
	v_pk_fma_f32 v[118:119], v[54:55], v[22:23], v[118:119]
	v_mov_b32_dpp v111, v127 row_shl:1 row_mask:0xf bank_mask:0xf
	v_pk_mul_f32 v[118:119], v[114:115], v[118:119]
	v_rcp_f32_e32 v114, v130
	v_rcp_f32_e32 v115, v131
	v_pk_mul_f32 v[128:129], v[124:125], v[12:13]
	v_pk_mul_f32 v[106:107], v[106:107], v[176:177]
	v_pk_fma_f32 v[126:127], v[126:127], v[10:11], v[128:129]
	v_pk_mul_f32 v[114:115], v[146:147], v[114:115]
	v_pk_fma_f32 v[126:127], v[52:53], v[14:15], v[126:127]
	v_add_u32_e32 v105, 0x2c00, v104
	v_pk_mul_f32 v[126:127], v[114:115], v[126:127]
	v_cvt_pk_f16_f32 v114, v106, v107
	v_pk_mul_f32 v[128:129], v[120:121], s[100:101] op_sel_hi:[1,0]
	v_exp_f32_e32 v128, v128
	v_exp_f32_e32 v129, v129
	v_cvt_pk_f16_f32 v115, v116, v117
	v_cvt_pk_f16_f32 v116, v118, v119
	v_cvt_pk_f16_f32 v117, v126, v127
	global_store_dwordx4 v105, v[114:117], s[14:15] nt
	v_pk_add_f32 v[128:129], v[128:129], 1.0 op_sel_hi:[1,0]
	v_rcp_f32_e32 v106, v128
	v_pk_mul_f32 v[116:117], v[122:123], s[100:101] op_sel_hi:[1,0]
	v_exp_f32_e32 v116, v116
	v_exp_f32_e32 v117, v117
	v_rcp_f32_e32 v107, v129
	v_pk_add_f32 v[116:117], v[116:117], 1.0 op_sel_hi:[1,0]
	v_rcp_f32_e32 v114, v116
	v_rcp_f32_e32 v115, v117
	v_pk_mul_f32 v[106:107], v[120:121], v[106:107]
	v_pk_mul_f32 v[116:117], v[80:81], s[100:101] op_sel_hi:[1,0]
	v_exp_f32_e32 v116, v116
	v_exp_f32_e32 v117, v117
	v_pk_mul_f32 v[100:101], v[106:107], v[100:101]
	v_pk_mul_f32 v[106:107], v[122:123], v[114:115]
	v_pk_add_f32 v[116:117], v[116:117], 1.0 op_sel_hi:[1,0]
	v_pk_mul_f32 v[102:103], v[106:107], v[102:103]
	v_rcp_f32_e32 v106, v116
	v_rcp_f32_e32 v107, v117
	v_pk_fma_f32 v[68:69], v[60:61], v[164:165], v[68:69]
	v_pk_fma_f32 v[60:61], v[60:61], v[160:161], v[168:169]
	v_pk_mul_f32 v[160:161], v[74:75], v[192:193]
	v_pk_mul_f32 v[70:71], v[208:209], v[70:71] op_sel_hi:[0,1]
	v_pk_fma_f32 v[82:83], v[82:83], v[162:163], v[160:161]
	v_pk_mul_f32 v[114:115], v[54:55], v[20:21]
	v_pk_fma_f32 v[82:83], v[70:71], v[166:167], v[82:83]
	v_pk_mul_f32 v[80:81], v[80:81], v[106:107]
	v_mul_f32_e32 v105, 0xbfb8aa3b, v82
	v_mul_f32_e32 v106, 0xbfb8aa3b, v83
	v_pk_fma_f32 v[112:113], v[112:113], v[18:19], v[114:115]
	v_exp_f32_e32 v105, v105
	v_exp_f32_e32 v114, v106
	v_pk_fma_f32 v[112:113], v[30:31], v[22:23], v[112:113]
	v_pk_mul_f32 v[160:161], v[70:71], v[192:193]
	v_pk_mul_f32 v[106:107], v[80:81], v[112:113]
	v_add_f32_e32 v80, 1.0, v105
	v_add_f32_e32 v81, 1.0, v114
	v_rcp_f32_e32 v80, v80
	v_rcp_f32_e32 v81, v81
	v_pk_mul_f32 v[112:113], v[52:53], v[12:13]
	v_add_u32_e32 v105, 0x5800, v104
	v_pk_fma_f32 v[112:113], v[124:125], v[10:11], v[112:113]
	v_pk_mul_f32 v[80:81], v[82:83], v[80:81]
	v_pk_fma_f32 v[112:113], v[28:29], v[14:15], v[112:113]
	v_cvt_pk_f16_f32 v82, v106, v107
	v_pk_mul_f32 v[112:113], v[80:81], v[112:113]
	v_cvt_pk_f16_f32 v80, v100, v101
	v_pk_mul_f32 v[100:101], v[48:49], s[100:101] op_sel_hi:[1,0]
	v_exp_f32_e32 v100, v100
	v_exp_f32_e32 v101, v101
	v_cvt_pk_f16_f32 v81, v102, v103
	v_cvt_pk_f16_f32 v83, v112, v113
	global_store_dwordx4 v105, v[80:83], s[14:15] nt
	v_pk_fma_f32 v[74:75], v[74:75], v[162:163], v[160:161]
	v_pk_mul_f32 v[160:161], v[66:67], v[192:193]
	v_pk_add_f32 v[80:81], v[100:101], 1.0 op_sel_hi:[1,0]
	v_rcp_f32_e32 v80, v80
	v_rcp_f32_e32 v81, v81
	v_pk_mul_f32 v[82:83], v[50:51], s[100:101] op_sel_hi:[1,0]
	v_exp_f32_e32 v82, v82
	v_pk_mul_f32 v[48:49], v[48:49], v[80:81]
	v_pk_mul_f32 v[80:81], v[72:73], s[100:101] op_sel_hi:[1,0]
	v_exp_f32_e32 v80, v80
	v_exp_f32_e32 v81, v81
	v_exp_f32_e32 v83, v83
	v_pk_add_f32 v[80:81], v[80:81], 1.0 op_sel_hi:[1,0]
	v_rcp_f32_e32 v80, v80
	v_rcp_f32_e32 v81, v81
	v_pk_add_f32 v[82:83], v[82:83], 1.0 op_sel_hi:[1,0]
	v_rcp_f32_e32 v82, v82
	v_rcp_f32_e32 v83, v83
	v_pk_fma_f32 v[74:75], v[66:67], v[166:167], v[74:75]
	v_pk_mul_f32 v[72:73], v[72:73], v[80:81]
	v_pk_mul_f32 v[80:81], v[74:75], s[100:101] op_sel_hi:[1,0]
	v_exp_f32_e32 v80, v80
	v_exp_f32_e32 v81, v81
	v_pk_mul_f32 v[50:51], v[50:51], v[82:83]
	v_pk_mul_f32 v[82:83], v[30:31], v[20:21]
	v_pk_mul_f32 v[48:49], v[48:49], v[96:97]
	v_pk_fma_f32 v[54:55], v[54:55], v[18:19], v[82:83]
; __device__ __forceinline__ float silu_f(float x) { return x * __builtin_amdgcn_rcpf(1.0f + __expf(-x)); }
;     __device__ __forceinline__ void operator()(Acc& acc, const Unit& u, int wr, int wc, int fr, int fq, LAS unsigned char* lds, int tid) const {
;     ...
;         for (int ai = 0; ai < 2; ++ai)
; #pragma unroll
;             for (int m = 0; m < 4; ++m) {
;                 f32x4 a[2];
; #pragma unroll
;                 for (int n = 0; n < 2; ++n)
; #pragma unroll
;                     for (int e = 0; e < 4; ++e) a[n][e] = silu_f(acc[ai][0][m][n][e]) * acc[ai][1][m][n][e];
;                 store_h8_nt((h16*)((char*)ACT + (((tok0 + tl0 + 4u * ai + m) * (unsigned)FF + colo) << 1)), a[0], a[1]);
;                 asm volatile("" ::: "memory");
	v_pk_mul_f32 v[50:51], v[50:51], v[98:99]
	v_pk_fma_f32 v[54:55], v[26:27], v[22:23], v[54:55]
	v_cvt_pk_f16_f32 v48, v48, v49
	v_pk_mul_f32 v[54:55], v[72:73], v[54:55]
	v_pk_add_f32 v[72:73], v[80:81], 1.0 op_sel_hi:[1,0]
	v_rcp_f32_e32 v72, v72
	v_rcp_f32_e32 v73, v73
	v_pk_mul_f32 v[80:81], v[28:29], v[12:13]
	v_cvt_pk_f16_f32 v49, v50, v51
	v_pk_fma_f32 v[52:53], v[52:53], v[10:11], v[80:81]
	v_pk_mul_f32 v[72:73], v[74:75], v[72:73]
	v_pk_fma_f32 v[52:53], v[24:25], v[14:15], v[52:53]
	v_cvt_pk_f16_f32 v50, v54, v55
	v_pk_mul_f32 v[52:53], v[72:73], v[52:53]
	v_add_u32_e32 v72, 0x8400, v104
	v_cvt_pk_f16_f32 v51, v52, v53
	v_pk_mul_f32 v[52:53], v[44:45], s[100:101] op_sel_hi:[1,0]
	v_exp_f32_e32 v52, v52
	v_exp_f32_e32 v53, v53
	global_store_dwordx4 v72, v[48:51], s[14:15] nt
	v_pk_fma_f32 v[70:71], v[70:71], v[162:163], v[160:161]
	v_pk_mul_f32 v[160:161], v[62:63], v[192:193]
	v_pk_add_f32 v[48:49], v[52:53], 1.0 op_sel_hi:[1,0]
	v_pk_mul_f32 v[50:51], v[46:47], s[100:101] op_sel_hi:[1,0]
	v_rcp_f32_e32 v48, v48
	v_exp_f32_e32 v50, v50
	v_exp_f32_e32 v51, v51
	v_rcp_f32_e32 v49, v49
	v_pk_fma_f32 v[70:71], v[62:63], v[166:167], v[70:71]
	v_pk_add_f32 v[50:51], v[50:51], 1.0 op_sel_hi:[1,0]
	v_pk_mul_f32 v[44:45], v[44:45], v[48:49]
	v_pk_mul_f32 v[48:49], v[68:69], s[100:101] op_sel_hi:[1,0]
	v_rcp_f32_e32 v50, v50
	v_rcp_f32_e32 v51, v51
	v_exp_f32_e32 v48, v48
	v_exp_f32_e32 v49, v49
	v_pk_mul_f32 v[44:45], v[44:45], v[92:93]
	v_pk_mul_f32 v[46:47], v[46:47], v[50:51]
	v_pk_add_f32 v[48:49], v[48:49], 1.0 op_sel_hi:[1,0]
	v_pk_mul_f32 v[50:51], v[26:27], v[20:21]
	v_rcp_f32_e32 v48, v48
	v_rcp_f32_e32 v49, v49
	v_pk_fma_f32 v[30:31], v[30:31], v[18:19], v[50:51]
	v_pk_mul_f32 v[50:51], v[70:71], s[100:101] op_sel_hi:[1,0]
	v_exp_f32_e32 v50, v50
	v_exp_f32_e32 v51, v51
	v_pk_fma_f32 v[30:31], v[16:17], v[22:23], v[30:31]
	v_pk_mul_f32 v[48:49], v[68:69], v[48:49]
	v_pk_mul_f32 v[46:47], v[46:47], v[94:95]
	v_pk_mul_f32 v[30:31], v[48:49], v[30:31]
	v_pk_add_f32 v[48:49], v[50:51], 1.0 op_sel_hi:[1,0]
	v_rcp_f32_e32 v48, v48
	v_rcp_f32_e32 v49, v49
	v_pk_mul_f32 v[50:51], v[24:25], v[12:13]
	v_cvt_pk_f16_f32 v30, v30, v31
	v_pk_fma_f32 v[28:29], v[28:29], v[10:11], v[50:51]
	v_pk_mul_f32 v[48:49], v[70:71], v[48:49]
	v_pk_fma_f32 v[28:29], v[8:9], v[14:15], v[28:29]
	v_add_u32_e32 v50, 0xb000, v104
	v_pk_mul_f32 v[48:49], v[48:49], v[28:29]
	v_cvt_pk_f16_f32 v28, v44, v45
	v_pk_mul_f32 v[44:45], v[40:41], s[100:101] op_sel_hi:[1,0]
	v_exp_f32_e32 v44, v44
	v_exp_f32_e32 v45, v45
	v_cvt_pk_f16_f32 v29, v46, v47
	v_cvt_pk_f16_f32 v31, v48, v49
	global_store_dwordx4 v50, v[28:31], s[14:15] nt
	v_pk_fma_f32 v[66:67], v[66:67], v[162:163], v[160:161]
	v_pk_fma_f32 v[90:91], v[78:79], v[194:195], v[90:91]
	v_pk_add_f32 v[28:29], v[44:45], 1.0 op_sel_hi:[1,0]
	v_pk_mul_f32 v[30:31], v[42:43], s[100:101] op_sel_hi:[1,0]
	v_rcp_f32_e32 v28, v28
	v_exp_f32_e32 v30, v30
	v_exp_f32_e32 v31, v31
	v_rcp_f32_e32 v29, v29
	v_pk_fma_f32 v[66:67], v[58:59], v[166:167], v[66:67]
	v_pk_add_f32 v[30:31], v[30:31], 1.0 op_sel_hi:[1,0]
	v_pk_mul_f32 v[28:29], v[40:41], v[28:29]
	v_pk_mul_f32 v[40:41], v[64:65], s[100:101] op_sel_hi:[1,0]
	v_rcp_f32_e32 v30, v30
	v_rcp_f32_e32 v31, v31
	v_exp_f32_e32 v40, v40
	v_exp_f32_e32 v41, v41
	v_pk_mul_f32 v[28:29], v[28:29], v[88:89]
	v_pk_mul_f32 v[30:31], v[42:43], v[30:31]
	v_pk_add_f32 v[40:41], v[40:41], 1.0 op_sel_hi:[1,0]
	v_pk_mul_f32 v[42:43], v[16:17], v[20:21]
	v_rcp_f32_e32 v40, v40
	v_rcp_f32_e32 v41, v41
	v_pk_fma_f32 v[26:27], v[26:27], v[18:19], v[42:43]
	v_pk_mul_f32 v[42:43], v[66:67], s[100:101] op_sel_hi:[1,0]
	v_exp_f32_e32 v42, v42
	v_exp_f32_e32 v43, v43
	v_pk_fma_f32 v[26:27], v[2:3], v[22:23], v[26:27]
	v_pk_mul_f32 v[40:41], v[64:65], v[40:41]
	v_pk_mul_f32 v[30:31], v[30:31], v[90:91]
	v_pk_mul_f32 v[26:27], v[40:41], v[26:27]
	v_pk_add_f32 v[40:41], v[42:43], 1.0 op_sel_hi:[1,0]
	v_rcp_f32_e32 v40, v40
	v_rcp_f32_e32 v41, v41
	v_pk_mul_f32 v[42:43], v[8:9], v[12:13]
	v_pk_fma_f32 v[60:61], v[234:235], v[164:165], v[60:61]
	v_pk_fma_f32 v[24:25], v[24:25], v[10:11], v[42:43]
	v_pk_mul_f32 v[40:41], v[66:67], v[40:41]
	v_pk_fma_f32 v[24:25], v[4:5], v[14:15], v[24:25]
	v_add_u32_e32 v42, 0xdc00, v104
	v_pk_mul_f32 v[40:41], v[40:41], v[24:25]
	v_cvt_pk_f16_f32 v24, v28, v29
; #define PG8_BAR __builtin_amdgcn_s_barrier()
; __device__ __forceinline__ float silu_f(float x) { return x * __builtin_amdgcn_rcpf(1.0f + __expf(-x)); }
; template <class Prob, class Epi, bool I8 = false, bool ALIGN_EPI = true, bool SP2 = true>
; __device__ __forceinline__ void gemm_phase(LAS unsigned char* lds, int wave, const Prob& P, const Epi& E) {
;     ...
;         cur = nxt; cA = nA; cB = nB; ++ui;
;         if constexpr (ALIGN_EPI) { if (wr == 1) PG8_BAR; }
;     __device__ __forceinline__ void operator()(Acc& acc, const Unit& u, int wr, int wc, int fr, int fq, LAS unsigned char* lds, int tid) const {
;     ...
;         for (int ai = 0; ai < 2; ++ai)
; #pragma unroll
;             for (int m = 0; m < 4; ++m) {
;                 f32x4 a[2];
; #pragma unroll
;                 for (int n = 0; n < 2; ++n)
; #pragma unroll
;                     for (int e = 0; e < 4; ++e) a[n][e] = silu_f(acc[ai][0][m][n][e]) * acc[ai][1][m][n][e];
;                 store_h8_nt((h16*)((char*)ACT + (((tok0 + tl0 + 4u * ai + m) * (unsigned)FF + colo) << 1)), a[0], a[1]);
;                 asm volatile("" ::: "memory");
	v_pk_mul_f32 v[28:29], v[36:37], s[100:101] op_sel_hi:[1,0]
	v_exp_f32_e32 v28, v28
	v_exp_f32_e32 v29, v29
	v_cvt_pk_f16_f32 v25, v30, v31
	v_cvt_pk_f16_f32 v26, v26, v27
	v_cvt_pk_f16_f32 v27, v40, v41
	global_store_dwordx4 v42, v[24:27], s[14:15] nt
	v_pk_mul_f32 v[160:161], v[58:59], v[192:193]
	v_pk_mul_f32 v[30:31], v[2:3], v[20:21]
	v_pk_add_f32 v[24:25], v[28:29], 1.0 op_sel_hi:[1,0]
	v_pk_mul_f32 v[28:29], v[60:61], s[100:101] op_sel_hi:[1,0]
	v_exp_f32_e32 v28, v28
	v_exp_f32_e32 v29, v29
	v_pk_fma_f32 v[62:63], v[62:63], v[162:163], v[160:161]
	v_pk_fma_f32 v[62:63], v[230:231], v[166:167], v[62:63]
	v_pk_add_f32 v[28:29], v[28:29], 1.0 op_sel_hi:[1,0]
	v_pk_mul_f32 v[26:27], v[38:39], s[100:101] op_sel_hi:[1,0]
	v_rcp_f32_e32 v28, v28
	v_rcp_f32_e32 v29, v29
	v_pk_fma_f32 v[16:17], v[16:17], v[18:19], v[30:31]
	v_pk_mul_f32 v[30:31], v[62:63], s[100:101] op_sel_hi:[1,0]
	v_exp_f32_e32 v26, v26
	v_exp_f32_e32 v27, v27
	v_exp_f32_e32 v30, v30
	v_exp_f32_e32 v31, v31
	v_pk_fma_f32 v[16:17], v[6:7], v[22:23], v[16:17]
	v_pk_mul_f32 v[28:29], v[60:61], v[28:29]
	v_pk_add_f32 v[26:27], v[26:27], 1.0 op_sel_hi:[1,0]
	v_pk_mul_f32 v[16:17], v[28:29], v[16:17]
	v_pk_add_f32 v[28:29], v[30:31], 1.0 op_sel_hi:[1,0]
	v_rcp_f32_e32 v24, v24
	v_rcp_f32_e32 v25, v25
	v_rcp_f32_e32 v26, v26
	v_rcp_f32_e32 v27, v27
	v_rcp_f32_e32 v28, v28
	v_rcp_f32_e32 v29, v29
	v_pk_mul_f32 v[30:31], v[4:5], v[12:13]
	v_pk_fma_f32 v[86:87], v[238:239], v[194:195], v[86:87]
	v_pk_fma_f32 v[8:9], v[8:9], v[10:11], v[30:31]
	v_pk_mul_f32 v[24:25], v[36:37], v[24:25]
	v_pk_mul_f32 v[26:27], v[38:39], v[26:27]
	v_pk_fma_f32 v[8:9], v[0:1], v[14:15], v[8:9]
	v_pk_mul_f32 v[28:29], v[62:63], v[28:29]
	v_pk_mul_f32 v[24:25], v[24:25], v[84:85]
	v_pk_mul_f32 v[26:27], v[26:27], v[86:87]
	v_pk_mul_f32 v[8:9], v[28:29], v[8:9]
	v_pk_fma_f32 v[56:57], v[164:165], v[172:173], v[56:57]
	v_add_u32_e32 v28, 0x10800, v104
	v_cvt_pk_f16_f32 v24, v24, v25
	v_cvt_pk_f16_f32 v25, v26, v27
	v_cvt_pk_f16_f32 v26, v16, v17
	v_cvt_pk_f16_f32 v27, v8, v9
	global_store_dwordx4 v28, v[24:27], s[14:15] nt
	v_pk_mul_f32 v[58:59], v[58:59], v[162:163]
	s_nop 0
	v_pk_mul_f32 v[24:25], v[56:57], s[100:101] op_sel_hi:[1,0]
	v_exp_f32_e32 v24, v24
	v_exp_f32_e32 v25, v25
	v_pk_fma_f32 v[58:59], v[230:231], v[192:193], v[58:59]
	v_pk_mul_f32 v[8:9], v[32:33], s[100:101] op_sel_hi:[1,0]
	v_pk_fma_f32 v[58:59], v[166:167], v[174:175], v[58:59]
	v_pk_add_f32 v[24:25], v[24:25], 1.0 op_sel_hi:[1,0]
	v_pk_mul_f32 v[16:17], v[34:35], s[100:101] op_sel_hi:[1,0]
	v_rcp_f32_e32 v24, v24
	v_rcp_f32_e32 v25, v25
	v_pk_mul_f32 v[2:3], v[2:3], v[18:19]
	v_pk_mul_f32 v[18:19], v[58:59], s[100:101] op_sel_hi:[1,0]
	v_exp_f32_e32 v8, v8
	v_exp_f32_e32 v9, v9
	v_exp_f32_e32 v16, v16
	v_exp_f32_e32 v17, v17
	v_exp_f32_e32 v18, v18
	v_exp_f32_e32 v19, v19
	v_mov_b32_dpp v108, v134 row_shl:1 row_mask:0xf bank_mask:0xf
	v_mov_b32_dpp v109, v135 row_shl:1 row_mask:0xf bank_mask:0xf
	v_pk_fma_f32 v[2:3], v[6:7], v[20:21], v[2:3]
	v_pk_mul_f32 v[6:7], v[56:57], v[24:25]
	v_pk_fma_f32 v[2:3], v[22:23], v[108:109], v[2:3]
	v_pk_add_f32 v[8:9], v[8:9], 1.0 op_sel_hi:[1,0]
	v_pk_add_f32 v[16:17], v[16:17], 1.0 op_sel_hi:[1,0]
	v_pk_mul_f32 v[2:3], v[6:7], v[2:3]
	v_pk_add_f32 v[6:7], v[18:19], 1.0 op_sel_hi:[1,0]
	v_rcp_f32_e32 v8, v8
	v_rcp_f32_e32 v9, v9
	v_rcp_f32_e32 v16, v16
	v_rcp_f32_e32 v17, v17
	v_rcp_f32_e32 v6, v6
	v_rcp_f32_e32 v7, v7
	v_pk_mul_f32 v[78:79], v[78:79], v[214:215]
	v_pk_mul_f32 v[4:5], v[4:5], v[10:11]
	v_pk_fma_f32 v[78:79], v[238:239], v[198:199], v[78:79]
	v_pk_fma_f32 v[0:1], v[0:1], v[12:13], v[4:5]
	v_pk_fma_f32 v[78:79], v[194:195], v[206:207], v[78:79]
	v_pk_mul_f32 v[8:9], v[32:33], v[8:9]
	v_pk_mul_f32 v[16:17], v[34:35], v[16:17]
	v_pk_fma_f32 v[0:1], v[14:15], v[110:111], v[0:1]
	v_pk_mul_f32 v[4:5], v[58:59], v[6:7]
	v_pk_mul_f32 v[8:9], v[8:9], v[76:77]
	v_pk_mul_f32 v[16:17], v[16:17], v[78:79]
	v_pk_mul_f32 v[4:5], v[4:5], v[0:1]
	v_add_u32_e32 v6, 0x13400, v104
	v_cvt_pk_f16_f32 v0, v8, v9
	v_cvt_pk_f16_f32 v1, v16, v17
	v_cvt_pk_f16_f32 v2, v2, v3
	v_cvt_pk_f16_f32 v3, v4, v5
	global_store_dwordx4 v6, v[0:3], s[14:15] nt
	s_cmp_eq_u32 s101, 0
	s_cbranch_scc1 .Lh1065_exit
	s_cmp_eq_u64 s[16:17], 0
	s_cbranch_scc1 .Lpt_w0
	s_setprio 1
	s_barrier
	s_branch .Lpeel_1065
.Lpt_w0:
	s_setprio 0
	s_branch .Lpeel_1065
